# v008 + next-unit scheduler arithmetic moved from the per-unit header into the peeled first MFMA block (P1/P3/P7/P12)
# speedup vs baseline: 1.0051x; 1.0012x over previous
; #define PG8_STAGE(bufoff, gbase, voff) do { _Pragma("unroll") for (int _i = 0; _i < 2; ++_i) \
;         __builtin_amdgcn_global_load_lds((const unsigned*)((const char*)(gbase) + (voff)[_i]), (PG8_LAS unsigned*)(lds + (bufoff) + ldsw + _i * 8192), 16, 0, PG8_LOAD_AUX); } while (0)
; #define PG8_LDA(dst, b, h) do { _Pragma("unroll") for (int m = 0; m < 4; ++m) _Pragma("unroll") for (int k = 0; k < 2; ++k) dst[m][k] = *(const PG8_LAS bf16x8*)(lds + PG8_SA(b, h) + aoff + m * 2048 + k * 1024); } while (0)
; #define PG8_LDB(dst, b, h) do { _Pragma("unroll") for (int n = 0; n < 2; ++n) _Pragma("unroll") for (int k = 0; k < 2; ++k) dst[n][k] = *(const PG8_LAS bf16x8*)(lds + PG8_SB(b, h) + boff + n * 2048 + k * 1024); } while (0)
;     __host__ __device__ bool next(int i, Unit& u) const {
;         const long L = (long)i * G + c; if (L >= nwg) return false;
;         int wgid = (int)L; { const int q = nwg / NXCD, r = nwg % NXCD, xcd = wgid % NXCD, off = wgid / NXCD; wgid = (xcd < r ? xcd * (q + 1) : r * (q + 1) + (xcd - r) * q) + off; }
;         const int nig = WGM * nN, gid = wgid / nig, fm = gid * WGM, gsz = (nM - fm) < WGM ? (nM - fm) : WGM;
;         u.pm = fm + ((wgid % nig) % gsz); u.pn = (wgid % nig) / gsz; return true;
; template <class Epi, class Sched, bool ALIGN_EPI = false, bool SP2 = false>
; __device__ __forceinline__ void gemm_phase(PG8_LAS unsigned char* lds, const Gemm g, const Sched& S, const Epi& E) {
;     ...
;         const bool has_next = S.next(ui + 1, nxt);
;         const char* nA = has_next ? (const char*)g.A + (size_t)nxt.pm * tstepA + (size_t)nxt.pn * apn : cA; const char* nB = has_next ? (const char*)g.Bt + (size_t)nxt.pn * tstepB : cB;
;         for (int t = 0; t < nt; t += 2) {
;             const bool last = (t == nt - 2);
;             const char* a1 = cA + (size_t)(t + 1) * kstep;
;             const char* a2 = last ? nA : cA + (size_t)(t + 2) * kstep; const char* b2 = last ? nB : cB + (size_t)(t + 2) * kstep;
;             const char* a3 = a2 + kstep; const char* b3 = b2 + kstep;
;             if (last && has_next) S.a_ready(nxt);
;             if constexpr (SP2) {
;             PG8_LDB(B0, 0, 0); PG8_LDB(B1, 0, 1); PG8_SCHED; PG8_LDA(At, 0, 0); PG8_STAGE(PG8_SA(1, 1), a1 + hstepA, voffA);
;             PG8_WAIT_V(8); PG8_WAIT_L(0); PG8_BAR; PG8_MMA(0, 0, At, B0); PG8_MMA(0, 1, At, B1); PG8_BAR; PG8_SCHED;
.LBB0_212:
	s_add_u32 s20, s20, 0x40080
	s_addc_u32 s21, s21, 0
	s_add_u32 s26, s22, 0x100
	s_addc_u32 s27, s23, 0
	s_mov_b32 s28, -2
	ds_read_b128 v[162:165], v158
	ds_read_b128 v[166:169], v158 offset:1024
	ds_read_b128 v[170:173], v158 offset:2048
	ds_read_b128 v[174:177], v158 offset:3072
	ds_read_b128 v[178:181], v159
	ds_read_b128 v[182:185], v159 offset:1024
	ds_read_b128 v[186:189], v159 offset:2048
	ds_read_b128 v[190:193], v159 offset:3072
	s_add_u32 s22, s20, 0xfffc0080
	s_addc_u32 s23, s21, -1
	s_cmp_eq_u32 s28, 12
	s_cselect_b32 s35, s17, s23
	s_cselect_b32 s34, s24, s22
	s_cselect_b32 s23, s15, s27
	s_cselect_b32 s22, s25, s26
	v_lshl_add_u64 v[226:227], s[20:21], 0, v[138:139]
	s_add_i32 m0, s42, 0xc000
	ds_read_b128 v[194:197], v160
	ds_read_b128 v[198:201], v160 offset:1024
	ds_read_b128 v[202:205], v160 offset:2048
	ds_read_b128 v[206:209], v160 offset:3072
	ds_read_b128 v[210:213], v160 offset:4096
	ds_read_b128 v[214:217], v160 offset:5120
	ds_read_b128 v[218:221], v160 offset:6144
	ds_read_b128 v[222:225], v160 offset:7168
	global_load_lds_dwordx4 v[226:227], off
	v_lshl_add_u64 v[226:227], s[20:21], 0, v[140:141]
	s_add_i32 m0, s42, 0xe000
	s_nop 0
	global_load_lds_dwordx4 v[226:227], off
	s_waitcnt vmcnt(8)
	s_waitcnt lgkmcnt(0)
	s_barrier
	s_waitcnt lgkmcnt(0)
	v_mfma_f32_16x16x32_bf16 v[124:127], v[162:165], v[194:197], 0
	s_add_i32 s46, s46, 1
	s_mul_i32 s4, s46, s47
	v_mfma_f32_16x16x32_bf16 v[120:123], v[170:173], v[194:197], 0
	s_mul_hi_u32 s5, s46, s50
	s_add_i32 s5, s5, s4
	v_mfma_f32_16x16x32_bf16 v[108:111], v[162:165], v[202:205], 0
	s_mul_i32 s4, s46, s50
	v_readlane_b32 s15, v239, 0
	v_mfma_f32_16x16x32_bf16 v[104:107], v[170:173], v[202:205], 0
	s_add_u32 s18, s4, s15
	s_addc_u32 s19, s5, s36
	v_mfma_f32_16x16x32_bf16 v[92:95], v[162:165], v[210:213], 0
	s_cmp_lt_u32 s18, 0x900
	s_cselect_b64 s[4:5], -1, 0
	v_mfma_f32_16x16x32_bf16 v[88:91], v[170:173], v[210:213], 0
	s_ashr_i32 s14, s18, 31
	s_lshr_b32 s14, s14, 29
	v_mfma_f32_16x16x32_bf16 v[76:79], v[162:165], v[218:221], 0
	s_add_i32 s14, s18, s14
	s_ashr_i32 s15, s14, 3
	v_mfma_f32_16x16x32_bf16 v[72:75], v[170:173], v[218:221], 0
	s_and_b32 s14, s14, -8
	s_sub_i32 s14, s18, s14
	v_mfma_f32_16x16x32_bf16 v[124:127], v[166:169], v[198:201], v[124:127]
	s_cmp_lt_i32 s14, 0
	s_cselect_b32 s16, s37, 0x120
	v_mfma_f32_16x16x32_bf16 v[120:123], v[174:177], v[198:201], v[120:123]
	s_mul_i32 s14, s14, s16
	s_add_i32 s14, s14, s15
	v_mfma_f32_16x16x32_bf16 v[108:111], v[166:169], v[206:209], v[108:111]
	s_mul_hi_i32 s15, s14, 0x38e38e39
	s_lshr_b32 s16, s15, 31
	v_mfma_f32_16x16x32_bf16 v[104:107], v[174:177], v[206:209], v[104:107]
	s_ashr_i32 s15, s15, 5
	s_add_i32 s15, s15, s16
	v_mfma_f32_16x16x32_bf16 v[92:95], v[166:169], v[214:217], v[92:95]
	s_lshl_b32 s16, s15, 2
	s_sub_i32 s17, 64, s16
	v_mfma_f32_16x16x32_bf16 v[88:91], v[174:177], v[214:217], v[88:91]
	s_min_i32 s17, s17, 4
	s_mulk_i32 s15, 0x90
	v_mfma_f32_16x16x32_bf16 v[76:79], v[166:169], v[222:225], v[76:79]
	s_sub_i32 s15, s14, s15
	s_lshr_b32 s14, s15, 2
	v_mfma_f32_16x16x32_bf16 v[72:75], v[174:177], v[222:225], v[72:75]
	s_and_b32 s15, s15, 3
	s_add_i32 s16, s16, s15
	v_mfma_f32_16x16x32_bf16 v[116:119], v[178:181], v[194:197], 0
	s_ashr_i32 s17, s16, 31
	s_lshl_b64 s[18:19], s[16:17], 19
	v_mfma_f32_16x16x32_bf16 v[112:115], v[186:189], v[194:197], 0
	v_readlane_b32 s24, v239, 47
	v_readlane_b32 s25, v239, 48
	v_mfma_f32_16x16x32_bf16 v[100:103], v[178:181], v[202:205], 0
	s_add_u32 s18, s24, s18
	s_addc_u32 s19, s25, s19
	v_mfma_f32_16x16x32_bf16 v[96:99], v[186:189], v[202:205], 0
	s_sub_u32 s98, s20, 0x40080
	s_subb_u32 s99, s21, 0
	v_mfma_f32_16x16x32_bf16 v[84:87], v[178:181], v[210:213], 0
	s_cmp_lg_u64 s[4:5], 0
	s_cselect_b32 s17, s19, s99
	v_mfma_f32_16x16x32_bf16 v[80:83], v[186:189], v[210:213], 0
	s_cselect_b32 s24, s18, s98
	s_ashr_i32 s15, s14, 31
	v_mfma_f32_16x16x32_bf16 v[68:71], v[178:181], v[218:221], 0
	s_lshl_b64 s[98:99], s[14:15], 19
	s_add_u32 s40, s64, s98
	v_mfma_f32_16x16x32_bf16 v[64:67], v[186:189], v[218:221], 0
	s_addc_u32 s41, s65, s99
	s_sub_u32 s98, s26, 0x100
	v_mfma_f32_16x16x32_bf16 v[116:119], v[182:185], v[198:201], v[116:119]
	s_subb_u32 s99, s27, 0
	s_cmp_lg_u64 s[4:5], 0
	v_mfma_f32_16x16x32_bf16 v[112:115], v[190:193], v[198:201], v[112:115]
	s_cselect_b32 s15, s41, s99
	s_cselect_b32 s25, s40, s98
	v_mfma_f32_16x16x32_bf16 v[100:103], v[182:185], v[206:209], v[100:103]
	v_mfma_f32_16x16x32_bf16 v[96:99], v[190:193], v[206:209], v[96:99]
	v_mfma_f32_16x16x32_bf16 v[84:87], v[182:185], v[214:217], v[84:87]
	v_mfma_f32_16x16x32_bf16 v[80:83], v[190:193], v[214:217], v[80:83]
	v_mfma_f32_16x16x32_bf16 v[68:71], v[182:185], v[222:225], v[68:71]
	v_mfma_f32_16x16x32_bf16 v[64:67], v[190:193], v[222:225], v[64:67]
	s_barrier
; #define PG8_STAGE(bufoff, gbase, voff) do { _Pragma("unroll") for (int _i = 0; _i < 2; ++_i) \
;         __builtin_amdgcn_global_load_lds((const unsigned*)((const char*)(gbase) + (voff)[_i]), (PG8_LAS unsigned*)(lds + (bufoff) + ldsw + _i * 8192), 16, 0, PG8_LOAD_AUX); } while (0)
; #define PG8_LDA(dst, b, h) do { _Pragma("unroll") for (int m = 0; m < 4; ++m) _Pragma("unroll") for (int k = 0; k < 2; ++k) dst[m][k] = *(const PG8_LAS bf16x8*)(lds + PG8_SA(b, h) + aoff + m * 2048 + k * 1024); } while (0)
; #define PG8_MMA(ai, bj, At, Bt) do { __builtin_amdgcn_s_setprio(1); _Pragma("unroll") for (int m = 0; m < 4; ++m) _Pragma("unroll") for (int n = 0; n < 2; ++n) _Pragma("unroll") for (int k = 0; k < 2; ++k) \
;         acc[ai][bj][m][n] = __builtin_amdgcn_mfma_f32_16x16x32_bf16(Bt[n][k], At[m][k], acc[ai][bj][m][n], 0, 0, 0); __builtin_amdgcn_s_setprio(0); } while (0)
; #define PG8_WAIT_V(n) asm volatile("s_waitcnt vmcnt(" #n ")" ::: "memory")
; #define PG8_WAIT_L(n) asm volatile("s_waitcnt lgkmcnt(" #n ")" ::: "memory")
; #define PG8_BAR __builtin_amdgcn_s_barrier()
; #define PG8_SCHED __builtin_amdgcn_sched_barrier(0)
; template <class Epi, class Sched, bool ALIGN_EPI = false, bool SP2 = false>
; __device__ __forceinline__ void gemm_phase(PG8_LAS unsigned char* lds, const Gemm g, const Sched& S, const Epi& E) {
;     ...
;             PG8_LDA(At, 0, 1); PG8_STAGE(PG8_SB(0, 0), b2, voffB); PG8_STAGE(PG8_SB(0, 1), b2 + hstepB, voffB); PG8_STAGE(PG8_SA(0, 0), a2, voffA);
;             PG8_WAIT_V(8); PG8_WAIT_L(0); PG8_BAR; PG8_MMA(1, 0, At, B0); PG8_MMA(1, 1, At, B1); PG8_BAR; PG8_SCHED;
	s_add_i32 s29, s51, s33
	v_lshl_add_u64 v[226:227], s[22:23], 0, v[130:131]
	s_mov_b32 m0, s29
	ds_read_b128 v[194:197], v160 offset:16384
	ds_read_b128 v[198:201], v160 offset:17408
	ds_read_b128 v[202:205], v160 offset:18432
	ds_read_b128 v[206:209], v160 offset:19456
	ds_read_b128 v[210:213], v160 offset:20480
	ds_read_b128 v[214:217], v160 offset:21504
	ds_read_b128 v[218:221], v160 offset:22528
	ds_read_b128 v[222:225], v160 offset:23552
	global_load_lds_dwordx4 v[226:227], off
	s_add_i32 m0, s29, 0x2000
	s_add_u32 s30, s22, 0x10000
	v_lshl_add_u64 v[228:229], s[22:23], 0, v[134:135]
	s_addc_u32 s31, s23, 0
	s_add_i32 s29, s52, s33
	global_load_lds_dwordx4 v[228:229], off
	v_lshl_add_u64 v[230:231], s[30:31], 0, v[130:131]
	s_mov_b32 m0, s29
	v_lshl_add_u64 v[232:233], s[34:35], 0, v[132:133]
	global_load_lds_dwordx4 v[230:231], off
	v_lshl_add_u64 v[230:231], s[30:31], 0, v[134:135]
	s_add_i32 m0, s29, 0x2000
	s_nop 0
	global_load_lds_dwordx4 v[230:231], off
	v_lshl_add_u64 v[230:231], s[34:35], 0, v[128:129]
	s_mov_b32 m0, s42
	s_nop 0
	global_load_lds_dwordx4 v[230:231], off
	s_mov_b32 m0, s43
	s_nop 0
	global_load_lds_dwordx4 v[232:233], off
	s_waitcnt vmcnt(8)
	s_waitcnt lgkmcnt(0)
	s_barrier
	s_waitcnt lgkmcnt(0)
	v_mfma_f32_16x16x32_bf16 v[60:63], v[162:165], v[194:197], 0
	v_mfma_f32_16x16x32_bf16 v[56:59], v[170:173], v[194:197], 0
	v_mfma_f32_16x16x32_bf16 v[44:47], v[162:165], v[202:205], 0
	v_mfma_f32_16x16x32_bf16 v[40:43], v[170:173], v[202:205], 0
	v_mfma_f32_16x16x32_bf16 v[28:31], v[162:165], v[210:213], 0
	v_mfma_f32_16x16x32_bf16 v[24:27], v[170:173], v[210:213], 0
	v_mfma_f32_16x16x32_bf16 v[12:15], v[162:165], v[218:221], 0
	v_mfma_f32_16x16x32_bf16 v[8:11], v[170:173], v[218:221], 0
	v_mfma_f32_16x16x32_bf16 v[60:63], v[166:169], v[198:201], v[60:63]
	v_mfma_f32_16x16x32_bf16 v[56:59], v[174:177], v[198:201], v[56:59]
	v_mfma_f32_16x16x32_bf16 v[44:47], v[166:169], v[206:209], v[44:47]
	v_mfma_f32_16x16x32_bf16 v[40:43], v[174:177], v[206:209], v[40:43]
	v_mfma_f32_16x16x32_bf16 v[28:31], v[166:169], v[214:217], v[28:31]
	v_mfma_f32_16x16x32_bf16 v[24:27], v[174:177], v[214:217], v[24:27]
	v_mfma_f32_16x16x32_bf16 v[12:15], v[166:169], v[222:225], v[12:15]
	v_mfma_f32_16x16x32_bf16 v[8:11], v[174:177], v[222:225], v[8:11]
	v_mfma_f32_16x16x32_bf16 v[52:55], v[178:181], v[194:197], 0
	v_mfma_f32_16x16x32_bf16 v[48:51], v[186:189], v[194:197], 0
	v_mfma_f32_16x16x32_bf16 v[36:39], v[178:181], v[202:205], 0
	v_mfma_f32_16x16x32_bf16 v[32:35], v[186:189], v[202:205], 0
	v_mfma_f32_16x16x32_bf16 v[20:23], v[178:181], v[210:213], 0
	v_mfma_f32_16x16x32_bf16 v[16:19], v[186:189], v[210:213], 0
	v_mfma_f32_16x16x32_bf16 v[4:7], v[178:181], v[218:221], 0
	v_mfma_f32_16x16x32_bf16 v[0:3], v[186:189], v[218:221], 0
	v_mfma_f32_16x16x32_bf16 v[52:55], v[182:185], v[198:201], v[52:55]
	v_mfma_f32_16x16x32_bf16 v[48:51], v[190:193], v[198:201], v[48:51]
	v_mfma_f32_16x16x32_bf16 v[36:39], v[182:185], v[206:209], v[36:39]
	v_mfma_f32_16x16x32_bf16 v[32:35], v[190:193], v[206:209], v[32:35]
	v_mfma_f32_16x16x32_bf16 v[20:23], v[182:185], v[214:217], v[20:23]
	v_mfma_f32_16x16x32_bf16 v[16:19], v[190:193], v[214:217], v[16:19]
	v_mfma_f32_16x16x32_bf16 v[4:7], v[182:185], v[222:225], v[4:7]
	v_mfma_f32_16x16x32_bf16 v[0:3], v[190:193], v[222:225], v[0:3]
	s_barrier
	s_branch .Lkmid_P1

; #define PG8_STAGE(bufoff, gbase, voff) do { _Pragma("unroll") for (int _i = 0; _i < 2; ++_i) \
;         __builtin_amdgcn_global_load_lds((const unsigned*)((const char*)(gbase) + (voff)[_i]), (PG8_LAS unsigned*)(lds + (bufoff) + ldsw + _i * 8192), 16, 0, PG8_LOAD_AUX); } while (0)
; #define PG8_LDA(dst, b, h) do { _Pragma("unroll") for (int m = 0; m < 4; ++m) _Pragma("unroll") for (int k = 0; k < 2; ++k) dst[m][k] = *(const PG8_LAS bf16x8*)(lds + PG8_SA(b, h) + aoff + m * 2048 + k * 1024); } while (0)
; #define PG8_LDB(dst, b, h) do { _Pragma("unroll") for (int n = 0; n < 2; ++n) _Pragma("unroll") for (int k = 0; k < 2; ++k) dst[n][k] = *(const PG8_LAS bf16x8*)(lds + PG8_SB(b, h) + boff + n * 2048 + k * 1024); } while (0)
;     __host__ __device__ bool next(int i, Unit& u) const {
;         const long L = (long)i * G + c; if (L >= nwg) return false;
;         int wgid = (int)L; { const int q = nwg / NXCD, r = nwg % NXCD, xcd = wgid % NXCD, off = wgid / NXCD; wgid = (xcd < r ? xcd * (q + 1) : r * (q + 1) + (xcd - r) * q) + off; }
;         const int nig = WGM * nN, gid = wgid / nig, fm = gid * WGM, gsz = (nM - fm) < WGM ? (nM - fm) : WGM;
;         u.pm = fm + ((wgid % nig) % gsz); u.pn = (wgid % nig) / gsz; return true;
; template <class Epi, class Sched, bool ALIGN_EPI = false, bool SP2 = false>
; __device__ __forceinline__ void gemm_phase(PG8_LAS unsigned char* lds, const Gemm g, const Sched& S, const Epi& E) {
;     ...
;         const bool has_next = S.next(ui + 1, nxt);
;         const char* nA = has_next ? (const char*)g.A + (size_t)nxt.pm * tstepA + (size_t)nxt.pn * apn : cA; const char* nB = has_next ? (const char*)g.Bt + (size_t)nxt.pn * tstepB : cB;
;         for (int t = 0; t < nt; t += 2) {
;             const bool last = (t == nt - 2);
;             const char* a1 = cA + (size_t)(t + 1) * kstep;
;             const char* a2 = last ? nA : cA + (size_t)(t + 2) * kstep; const char* b2 = last ? nB : cB + (size_t)(t + 2) * kstep;
;             const char* a3 = a2 + kstep; const char* b3 = b2 + kstep;
;             if (last && has_next) S.a_ready(nxt);
;             if constexpr (SP2) {
;             PG8_LDB(B0, 0, 0); PG8_LDB(B1, 0, 1); PG8_SCHED; PG8_LDA(At, 0, 0); PG8_STAGE(PG8_SA(1, 1), a1 + hstepA, voffA);
;             PG8_WAIT_V(8); PG8_WAIT_L(0); PG8_BAR; PG8_MMA(0, 0, At, B0); PG8_MMA(0, 1, At, B1); PG8_BAR; PG8_SCHED;
.LBB0_366:
	s_add_u32 s20, s20, 0x40080
	s_addc_u32 s21, s21, 0
	s_add_u32 s26, s22, 0x100
	s_addc_u32 s27, s23, 0
	s_mov_b32 s28, -2
	ds_read_b128 v[162:165], v159
	ds_read_b128 v[166:169], v159 offset:1024
	ds_read_b128 v[170:173], v159 offset:2048
	ds_read_b128 v[174:177], v159 offset:3072
	ds_read_b128 v[178:181], v160
	ds_read_b128 v[182:185], v160 offset:1024
	ds_read_b128 v[186:189], v160 offset:2048
	ds_read_b128 v[190:193], v160 offset:3072
	s_add_u32 s22, s20, 0xfffc0080
	s_addc_u32 s23, s21, -1
	s_cmp_eq_u32 s28, 12
	s_cselect_b32 s35, s17, s23
	s_cselect_b32 s34, s24, s22
	s_cselect_b32 s23, s15, s27
	s_cselect_b32 s22, s25, s26
	v_lshl_add_u64 v[226:227], s[20:21], 0, v[138:139]
	s_add_i32 m0, s44, 0xc000
	ds_read_b128 v[194:197], v161
	ds_read_b128 v[198:201], v161 offset:1024
	ds_read_b128 v[202:205], v161 offset:2048
	ds_read_b128 v[206:209], v161 offset:3072
	ds_read_b128 v[210:213], v161 offset:4096
	ds_read_b128 v[214:217], v161 offset:5120
	ds_read_b128 v[218:221], v161 offset:6144
	ds_read_b128 v[222:225], v161 offset:7168
	global_load_lds_dwordx4 v[226:227], off
	v_lshl_add_u64 v[226:227], s[20:21], 0, v[140:141]
	s_add_i32 m0, s44, 0xe000
	s_nop 0
	global_load_lds_dwordx4 v[226:227], off
	s_waitcnt vmcnt(8)
	s_waitcnt lgkmcnt(0)
	s_barrier
	s_waitcnt lgkmcnt(0)
	v_mfma_f32_16x16x32_bf16 v[124:127], v[162:165], v[194:197], 0
	s_add_i32 s48, s48, 1
	s_mul_i32 s4, s48, s51
	v_mfma_f32_16x16x32_bf16 v[120:123], v[170:173], v[194:197], 0
	s_mul_hi_u32 s5, s48, s52
	s_add_i32 s5, s5, s4
	v_mfma_f32_16x16x32_bf16 v[108:111], v[162:165], v[202:205], 0
	s_mul_i32 s4, s48, s52
	v_readlane_b32 s15, v239, 0
	v_mfma_f32_16x16x32_bf16 v[104:107], v[170:173], v[202:205], 0
	s_add_u32 s18, s4, s15
	s_addc_u32 s19, s5, s42
	v_mfma_f32_16x16x32_bf16 v[92:95], v[162:165], v[210:213], 0
	s_cmp_lt_u32 s18, 0x900
	s_cselect_b64 s[4:5], -1, 0
	v_mfma_f32_16x16x32_bf16 v[88:91], v[170:173], v[210:213], 0
	s_ashr_i32 s14, s18, 31
	s_lshr_b32 s14, s14, 29
	v_mfma_f32_16x16x32_bf16 v[76:79], v[162:165], v[218:221], 0
	s_add_i32 s14, s18, s14
	s_ashr_i32 s15, s14, 3
	v_mfma_f32_16x16x32_bf16 v[72:75], v[170:173], v[218:221], 0
	s_and_b32 s14, s14, -8
	s_sub_i32 s14, s18, s14
	v_mfma_f32_16x16x32_bf16 v[124:127], v[166:169], v[198:201], v[124:127]
	s_cmp_lt_i32 s14, 0
	s_cselect_b32 s16, s43, 0x120
	v_mfma_f32_16x16x32_bf16 v[120:123], v[174:177], v[198:201], v[120:123]
	s_mul_i32 s14, s14, s16
	s_add_i32 s14, s14, s15
	v_mfma_f32_16x16x32_bf16 v[108:111], v[166:169], v[206:209], v[108:111]
	s_mul_hi_i32 s15, s14, 0x38e38e39
	s_lshr_b32 s16, s15, 31
	v_mfma_f32_16x16x32_bf16 v[104:107], v[174:177], v[206:209], v[104:107]
	s_ashr_i32 s15, s15, 5
	s_add_i32 s15, s15, s16
	v_mfma_f32_16x16x32_bf16 v[92:95], v[166:169], v[214:217], v[92:95]
	s_lshl_b32 s16, s15, 2
	s_sub_i32 s17, 64, s16
	v_mfma_f32_16x16x32_bf16 v[88:91], v[174:177], v[214:217], v[88:91]
	s_min_i32 s17, s17, 4
	s_mulk_i32 s15, 0x90
	v_mfma_f32_16x16x32_bf16 v[76:79], v[166:169], v[222:225], v[76:79]
	s_sub_i32 s15, s14, s15
	s_lshr_b32 s14, s15, 2
	v_mfma_f32_16x16x32_bf16 v[72:75], v[174:177], v[222:225], v[72:75]
	s_and_b32 s15, s15, 3
	s_add_i32 s16, s16, s15
	v_mfma_f32_16x16x32_bf16 v[116:119], v[178:181], v[194:197], 0
	s_ashr_i32 s17, s16, 31
	s_lshl_b64 s[18:19], s[16:17], 19
	v_mfma_f32_16x16x32_bf16 v[112:115], v[186:189], v[194:197], 0
	s_add_u32 s18, s33, s18
	s_addc_u32 s19, s36, s19
	v_mfma_f32_16x16x32_bf16 v[100:103], v[178:181], v[202:205], 0
	s_sub_u32 s98, s20, 0x40080
	s_subb_u32 s99, s21, 0
	v_mfma_f32_16x16x32_bf16 v[96:99], v[186:189], v[202:205], 0
	s_cmp_lg_u64 s[4:5], 0
	s_cselect_b32 s17, s19, s99
	v_mfma_f32_16x16x32_bf16 v[84:87], v[178:181], v[210:213], 0
	s_cselect_b32 s24, s18, s98
	s_ashr_i32 s15, s14, 31
	v_mfma_f32_16x16x32_bf16 v[80:83], v[186:189], v[210:213], 0
	s_lshl_b64 s[98:99], s[14:15], 19
	s_add_u32 s40, s64, s98
	v_mfma_f32_16x16x32_bf16 v[68:71], v[178:181], v[218:221], 0
	s_addc_u32 s41, s65, s99
	s_sub_u32 s98, s26, 0x100
	v_mfma_f32_16x16x32_bf16 v[64:67], v[186:189], v[218:221], 0
	s_subb_u32 s99, s27, 0
	s_cmp_lg_u64 s[4:5], 0
	v_mfma_f32_16x16x32_bf16 v[116:119], v[182:185], v[198:201], v[116:119]
	s_cselect_b32 s15, s41, s99
	s_cselect_b32 s25, s40, s98
	v_mfma_f32_16x16x32_bf16 v[112:115], v[190:193], v[198:201], v[112:115]
	v_mfma_f32_16x16x32_bf16 v[100:103], v[182:185], v[206:209], v[100:103]
	v_mfma_f32_16x16x32_bf16 v[96:99], v[190:193], v[206:209], v[96:99]
	v_mfma_f32_16x16x32_bf16 v[84:87], v[182:185], v[214:217], v[84:87]
	v_mfma_f32_16x16x32_bf16 v[80:83], v[190:193], v[214:217], v[80:83]
	v_mfma_f32_16x16x32_bf16 v[68:71], v[182:185], v[222:225], v[68:71]
	v_mfma_f32_16x16x32_bf16 v[64:67], v[190:193], v[222:225], v[64:67]
	s_barrier
; #define PG8_STAGE(bufoff, gbase, voff) do { _Pragma("unroll") for (int _i = 0; _i < 2; ++_i) \
;         __builtin_amdgcn_global_load_lds((const unsigned*)((const char*)(gbase) + (voff)[_i]), (PG8_LAS unsigned*)(lds + (bufoff) + ldsw + _i * 8192), 16, 0, PG8_LOAD_AUX); } while (0)
; #define PG8_LDA(dst, b, h) do { _Pragma("unroll") for (int m = 0; m < 4; ++m) _Pragma("unroll") for (int k = 0; k < 2; ++k) dst[m][k] = *(const PG8_LAS bf16x8*)(lds + PG8_SA(b, h) + aoff + m * 2048 + k * 1024); } while (0)
; #define PG8_MMA(ai, bj, At, Bt) do { __builtin_amdgcn_s_setprio(1); _Pragma("unroll") for (int m = 0; m < 4; ++m) _Pragma("unroll") for (int n = 0; n < 2; ++n) _Pragma("unroll") for (int k = 0; k < 2; ++k) \
;         acc[ai][bj][m][n] = __builtin_amdgcn_mfma_f32_16x16x32_bf16(Bt[n][k], At[m][k], acc[ai][bj][m][n], 0, 0, 0); __builtin_amdgcn_s_setprio(0); } while (0)
; #define PG8_WAIT_V(n) asm volatile("s_waitcnt vmcnt(" #n ")" ::: "memory")
; #define PG8_WAIT_L(n) asm volatile("s_waitcnt lgkmcnt(" #n ")" ::: "memory")
; #define PG8_BAR __builtin_amdgcn_s_barrier()
; #define PG8_SCHED __builtin_amdgcn_sched_barrier(0)
; template <class Epi, class Sched, bool ALIGN_EPI = false, bool SP2 = false>
; __device__ __forceinline__ void gemm_phase(PG8_LAS unsigned char* lds, const Gemm g, const Sched& S, const Epi& E) {
;     ...
;             PG8_LDA(At, 0, 1); PG8_STAGE(PG8_SB(0, 0), b2, voffB); PG8_STAGE(PG8_SB(0, 1), b2 + hstepB, voffB); PG8_STAGE(PG8_SA(0, 0), a2, voffA);
;             PG8_WAIT_V(8); PG8_WAIT_L(0); PG8_BAR; PG8_MMA(1, 0, At, B0); PG8_MMA(1, 1, At, B1); PG8_BAR; PG8_SCHED;
	s_add_i32 s29, s53, s37
	v_lshl_add_u64 v[226:227], s[22:23], 0, v[132:133]
	s_mov_b32 m0, s29
	ds_read_b128 v[194:197], v161 offset:16384
	ds_read_b128 v[198:201], v161 offset:17408
	ds_read_b128 v[202:205], v161 offset:18432
	ds_read_b128 v[206:209], v161 offset:19456
	ds_read_b128 v[210:213], v161 offset:20480
	ds_read_b128 v[214:217], v161 offset:21504
	ds_read_b128 v[218:221], v161 offset:22528
	ds_read_b128 v[222:225], v161 offset:23552
	global_load_lds_dwordx4 v[226:227], off
	s_add_i32 m0, s29, 0x2000
	s_add_u32 s30, s22, 0x10000
	v_lshl_add_u64 v[228:229], s[22:23], 0, v[128:129]
	s_addc_u32 s31, s23, 0
	s_add_i32 s29, s54, s37
	global_load_lds_dwordx4 v[228:229], off
	v_lshl_add_u64 v[230:231], s[30:31], 0, v[132:133]
	s_mov_b32 m0, s29
	v_lshl_add_u64 v[232:233], s[34:35], 0, v[130:131]
	global_load_lds_dwordx4 v[230:231], off
	v_lshl_add_u64 v[230:231], s[30:31], 0, v[128:129]
	s_add_i32 m0, s29, 0x2000
	s_nop 0
	global_load_lds_dwordx4 v[230:231], off
	v_lshl_add_u64 v[230:231], s[34:35], 0, v[134:135]
	s_mov_b32 m0, s44
	s_nop 0
	global_load_lds_dwordx4 v[230:231], off
	s_mov_b32 m0, s45
	s_nop 0
	global_load_lds_dwordx4 v[232:233], off
	s_waitcnt vmcnt(8)
	s_waitcnt lgkmcnt(0)
	s_barrier
	s_waitcnt lgkmcnt(0)
	v_mfma_f32_16x16x32_bf16 v[60:63], v[162:165], v[194:197], 0
	v_mfma_f32_16x16x32_bf16 v[56:59], v[170:173], v[194:197], 0
	v_mfma_f32_16x16x32_bf16 v[44:47], v[162:165], v[202:205], 0
	v_mfma_f32_16x16x32_bf16 v[40:43], v[170:173], v[202:205], 0
	v_mfma_f32_16x16x32_bf16 v[28:31], v[162:165], v[210:213], 0
	v_mfma_f32_16x16x32_bf16 v[24:27], v[170:173], v[210:213], 0
	v_mfma_f32_16x16x32_bf16 v[12:15], v[162:165], v[218:221], 0
	v_mfma_f32_16x16x32_bf16 v[8:11], v[170:173], v[218:221], 0
	v_mfma_f32_16x16x32_bf16 v[60:63], v[166:169], v[198:201], v[60:63]
	v_mfma_f32_16x16x32_bf16 v[56:59], v[174:177], v[198:201], v[56:59]
	v_mfma_f32_16x16x32_bf16 v[44:47], v[166:169], v[206:209], v[44:47]
	v_mfma_f32_16x16x32_bf16 v[40:43], v[174:177], v[206:209], v[40:43]
	v_mfma_f32_16x16x32_bf16 v[28:31], v[166:169], v[214:217], v[28:31]
	v_mfma_f32_16x16x32_bf16 v[24:27], v[174:177], v[214:217], v[24:27]
	v_mfma_f32_16x16x32_bf16 v[12:15], v[166:169], v[222:225], v[12:15]
	v_mfma_f32_16x16x32_bf16 v[8:11], v[174:177], v[222:225], v[8:11]
	v_mfma_f32_16x16x32_bf16 v[52:55], v[178:181], v[194:197], 0
	v_mfma_f32_16x16x32_bf16 v[48:51], v[186:189], v[194:197], 0
	v_mfma_f32_16x16x32_bf16 v[36:39], v[178:181], v[202:205], 0
	v_mfma_f32_16x16x32_bf16 v[32:35], v[186:189], v[202:205], 0
	v_mfma_f32_16x16x32_bf16 v[20:23], v[178:181], v[210:213], 0
	v_mfma_f32_16x16x32_bf16 v[16:19], v[186:189], v[210:213], 0
	v_mfma_f32_16x16x32_bf16 v[4:7], v[178:181], v[218:221], 0
	v_mfma_f32_16x16x32_bf16 v[0:3], v[186:189], v[218:221], 0
	v_mfma_f32_16x16x32_bf16 v[52:55], v[182:185], v[198:201], v[52:55]
	v_mfma_f32_16x16x32_bf16 v[48:51], v[190:193], v[198:201], v[48:51]
	v_mfma_f32_16x16x32_bf16 v[36:39], v[182:185], v[206:209], v[36:39]
	v_mfma_f32_16x16x32_bf16 v[32:35], v[190:193], v[206:209], v[32:35]
	v_mfma_f32_16x16x32_bf16 v[20:23], v[182:185], v[214:217], v[20:23]
	v_mfma_f32_16x16x32_bf16 v[16:19], v[190:193], v[214:217], v[16:19]
	v_mfma_f32_16x16x32_bf16 v[4:7], v[182:185], v[222:225], v[4:7]
	v_mfma_f32_16x16x32_bf16 v[0:3], v[190:193], v[222:225], v[0:3]
	s_barrier
	s_branch .Lkmid_P3

; #define PG8_STAGE(bufoff, gbase, voff) do { _Pragma("unroll") for (int _i = 0; _i < 2; ++_i) \
;         __builtin_amdgcn_global_load_lds((const unsigned*)((const char*)(gbase) + (voff)[_i]), (PG8_LAS unsigned*)(lds + (bufoff) + ldsw + _i * 8192), 16, 0, PG8_LOAD_AUX); } while (0)
; #define PG8_LDA(dst, b, h) do { _Pragma("unroll") for (int m = 0; m < 4; ++m) _Pragma("unroll") for (int k = 0; k < 2; ++k) dst[m][k] = *(const PG8_LAS bf16x8*)(lds + PG8_SA(b, h) + aoff + m * 2048 + k * 1024); } while (0)
; #define PG8_LDB(dst, b, h) do { _Pragma("unroll") for (int n = 0; n < 2; ++n) _Pragma("unroll") for (int k = 0; k < 2; ++k) dst[n][k] = *(const PG8_LAS bf16x8*)(lds + PG8_SB(b, h) + boff + n * 2048 + k * 1024); } while (0)
;     __host__ __device__ bool next(int i, Unit& u) const {
;         const long L = (long)i * G + c; if (L >= nwg) return false;
;         int wgid = (int)L; { const int q = nwg / NXCD, r = nwg % NXCD, xcd = wgid % NXCD, off = wgid / NXCD; wgid = (xcd < r ? xcd * (q + 1) : r * (q + 1) + (xcd - r) * q) + off; }
;         const int nig = WGM * nN, gid = wgid / nig, fm = gid * WGM, gsz = (nM - fm) < WGM ? (nM - fm) : WGM;
;         u.pm = fm + ((wgid % nig) % gsz); u.pn = (wgid % nig) / gsz; return true;
; template <class Epi, class Sched, bool ALIGN_EPI = false, bool SP2 = false>
; __device__ __forceinline__ void gemm_phase(PG8_LAS unsigned char* lds, const Gemm g, const Sched& S, const Epi& E) {
;     ...
;         const bool has_next = S.next(ui + 1, nxt);
;         const char* nA = has_next ? (const char*)g.A + (size_t)nxt.pm * tstepA + (size_t)nxt.pn * apn : cA; const char* nB = has_next ? (const char*)g.Bt + (size_t)nxt.pn * tstepB : cB;
;         for (int t = 0; t < nt; t += 2) {
;             const bool last = (t == nt - 2);
;             const char* a1 = cA + (size_t)(t + 1) * kstep;
;             const char* a2 = last ? nA : cA + (size_t)(t + 2) * kstep; const char* b2 = last ? nB : cB + (size_t)(t + 2) * kstep;
;             const char* a3 = a2 + kstep; const char* b3 = b2 + kstep;
;             if (last && has_next) S.a_ready(nxt);
;             if constexpr (SP2) {
;             PG8_LDB(B0, 0, 0); PG8_LDB(B1, 0, 1); PG8_SCHED; PG8_LDA(At, 0, 0); PG8_STAGE(PG8_SA(1, 1), a1 + hstepA, voffA);
;             PG8_WAIT_V(8); PG8_WAIT_L(0); PG8_BAR; PG8_MMA(0, 0, At, B0); PG8_MMA(0, 1, At, B1); PG8_BAR; PG8_SCHED;
.LBB0_669:
	s_add_u32 s20, s20, 0x40080
	s_addc_u32 s21, s21, 0
	s_add_u32 s26, s22, 0x100
	s_addc_u32 s27, s23, 0
	s_mov_b32 s28, -2
	ds_read_b128 v[146:149], v158
	ds_read_b128 v[164:167], v158 offset:1024
	ds_read_b128 v[168:171], v158 offset:2048
	ds_read_b128 v[172:175], v158 offset:3072
	ds_read_b128 v[176:179], v159
	ds_read_b128 v[180:183], v159 offset:1024
	ds_read_b128 v[184:187], v159 offset:2048
	ds_read_b128 v[188:191], v159 offset:3072
	s_add_u32 s22, s20, 0xfffc0080
	s_addc_u32 s23, s21, -1
	s_cmp_eq_u32 s28, 12
	s_cselect_b32 s35, s17, s23
	s_cselect_b32 s34, s24, s22
	s_cselect_b32 s23, s15, s27
	s_cselect_b32 s22, s25, s26
	v_lshl_add_u64 v[150:151], s[20:21], 0, v[138:139]
	s_add_i32 m0, s43, 0xc000
	ds_read_b128 v[192:195], v160
	ds_read_b128 v[196:199], v160 offset:1024
	ds_read_b128 v[200:203], v160 offset:2048
	ds_read_b128 v[204:207], v160 offset:3072
	ds_read_b128 v[208:211], v160 offset:4096
	ds_read_b128 v[212:215], v160 offset:5120
	ds_read_b128 v[216:219], v160 offset:6144
	ds_read_b128 v[220:223], v160 offset:7168
	global_load_lds_dwordx4 v[150:151], off
	v_lshl_add_u64 v[150:151], s[20:21], 0, v[140:141]
	s_add_i32 m0, s43, 0xe000
	s_nop 0
	global_load_lds_dwordx4 v[150:151], off
	s_waitcnt vmcnt(8)
	s_waitcnt lgkmcnt(0)
	s_barrier
	s_waitcnt lgkmcnt(0)
	v_mfma_f32_16x16x32_bf16 v[124:127], v[146:149], v[192:195], 0
	s_add_i32 s49, s49, 1
	s_mul_i32 s2, s49, s50
	v_mfma_f32_16x16x32_bf16 v[120:123], v[168:171], v[192:195], 0
	s_mul_hi_u32 s3, s49, s53
	s_add_i32 s3, s3, s2
	v_mfma_f32_16x16x32_bf16 v[108:111], v[146:149], v[200:203], 0
	s_mul_i32 s2, s49, s53
	v_readlane_b32 s15, v239, 0
	v_mfma_f32_16x16x32_bf16 v[104:107], v[168:171], v[200:203], 0
	s_add_u32 s18, s2, s15
	s_addc_u32 s19, s3, s41
	v_mfma_f32_16x16x32_bf16 v[92:95], v[146:149], v[208:211], 0
	s_cmp_lt_u32 s18, 0xb00
	s_cselect_b64 s[2:3], -1, 0
	v_mfma_f32_16x16x32_bf16 v[88:91], v[168:171], v[208:211], 0
	s_ashr_i32 s14, s18, 31
	s_lshr_b32 s14, s14, 29
	v_mfma_f32_16x16x32_bf16 v[76:79], v[146:149], v[216:219], 0
	s_add_i32 s14, s18, s14
	s_ashr_i32 s15, s14, 3
	v_mfma_f32_16x16x32_bf16 v[72:75], v[168:171], v[216:219], 0
	s_and_b32 s14, s14, -8
	s_sub_i32 s14, s18, s14
	v_mfma_f32_16x16x32_bf16 v[124:127], v[164:167], v[196:199], v[124:127]
	s_cmp_lt_i32 s14, 0
	s_cselect_b32 s16, s42, 0x160
	v_mfma_f32_16x16x32_bf16 v[120:123], v[172:175], v[196:199], v[120:123]
	s_mul_i32 s14, s14, s16
	s_add_i32 s14, s14, s15
	v_mfma_f32_16x16x32_bf16 v[108:111], v[164:167], v[204:207], v[108:111]
	s_mul_hi_i32 s15, s14, 0x2e8ba2e9
	s_lshr_b32 s16, s15, 31
	v_mfma_f32_16x16x32_bf16 v[104:107], v[172:175], v[204:207], v[104:107]
	s_ashr_i32 s15, s15, 4
	s_add_i32 s15, s15, s16
	v_mfma_f32_16x16x32_bf16 v[92:95], v[164:167], v[212:215], v[92:95]
	s_lshl_b32 s16, s15, 2
	s_sub_i32 s17, 0x80, s16
	v_mfma_f32_16x16x32_bf16 v[88:91], v[172:175], v[212:215], v[88:91]
	s_min_i32 s17, s17, 4
	s_mulk_i32 s15, 0x58
	v_mfma_f32_16x16x32_bf16 v[76:79], v[164:167], v[220:223], v[76:79]
	s_sub_i32 s15, s14, s15
	s_lshr_b32 s14, s15, 2
	v_mfma_f32_16x16x32_bf16 v[72:75], v[172:175], v[220:223], v[72:75]
	s_and_b32 s15, s15, 3
	s_add_i32 s16, s16, s15
	v_mfma_f32_16x16x32_bf16 v[116:119], v[176:179], v[192:195], 0
	s_ashr_i32 s17, s16, 31
	s_lshl_b64 s[18:19], s[16:17], 19
	v_mfma_f32_16x16x32_bf16 v[112:115], v[184:187], v[192:195], 0
	s_add_u32 s18, s30, s18
	s_addc_u32 s19, s31, s19
	v_mfma_f32_16x16x32_bf16 v[100:103], v[176:179], v[200:203], 0
	s_sub_u32 s98, s20, 0x40080
	s_subb_u32 s99, s21, 0
	v_mfma_f32_16x16x32_bf16 v[96:99], v[184:187], v[200:203], 0
	s_cmp_lg_u64 s[2:3], 0
	s_cselect_b32 s17, s19, s99
	v_mfma_f32_16x16x32_bf16 v[84:87], v[176:179], v[208:211], 0
	s_cselect_b32 s24, s18, s98
	s_ashr_i32 s15, s14, 31
	v_mfma_f32_16x16x32_bf16 v[80:83], v[184:187], v[208:211], 0
	s_lshl_b64 s[98:99], s[14:15], 19
	v_readlane_b32 s15, v239, 40
	v_mfma_f32_16x16x32_bf16 v[68:71], v[176:179], v[216:219], 0
	s_add_u32 s36, s15, s98
	v_readlane_b32 s15, v239, 41
	v_mfma_f32_16x16x32_bf16 v[64:67], v[184:187], v[216:219], 0
	s_addc_u32 s37, s15, s99
	s_sub_u32 s98, s26, 0x100
	v_mfma_f32_16x16x32_bf16 v[116:119], v[180:183], v[196:199], v[116:119]
	s_subb_u32 s99, s27, 0
	s_cmp_lg_u64 s[2:3], 0
	v_mfma_f32_16x16x32_bf16 v[112:115], v[188:191], v[196:199], v[112:115]
	s_cselect_b32 s15, s37, s99
	s_cselect_b32 s25, s36, s98
	v_mfma_f32_16x16x32_bf16 v[100:103], v[180:183], v[204:207], v[100:103]
	v_mfma_f32_16x16x32_bf16 v[96:99], v[188:191], v[204:207], v[96:99]
	v_mfma_f32_16x16x32_bf16 v[84:87], v[180:183], v[212:215], v[84:87]
	v_mfma_f32_16x16x32_bf16 v[80:83], v[188:191], v[212:215], v[80:83]
	v_mfma_f32_16x16x32_bf16 v[68:71], v[180:183], v[220:223], v[68:71]
	v_mfma_f32_16x16x32_bf16 v[64:67], v[188:191], v[220:223], v[64:67]
	s_barrier
; #define PG8_STAGE(bufoff, gbase, voff) do { _Pragma("unroll") for (int _i = 0; _i < 2; ++_i) \
;         __builtin_amdgcn_global_load_lds((const unsigned*)((const char*)(gbase) + (voff)[_i]), (PG8_LAS unsigned*)(lds + (bufoff) + ldsw + _i * 8192), 16, 0, PG8_LOAD_AUX); } while (0)
; #define PG8_LDA(dst, b, h) do { _Pragma("unroll") for (int m = 0; m < 4; ++m) _Pragma("unroll") for (int k = 0; k < 2; ++k) dst[m][k] = *(const PG8_LAS bf16x8*)(lds + PG8_SA(b, h) + aoff + m * 2048 + k * 1024); } while (0)
; #define PG8_MMA(ai, bj, At, Bt) do { __builtin_amdgcn_s_setprio(1); _Pragma("unroll") for (int m = 0; m < 4; ++m) _Pragma("unroll") for (int n = 0; n < 2; ++n) _Pragma("unroll") for (int k = 0; k < 2; ++k) \
;         acc[ai][bj][m][n] = __builtin_amdgcn_mfma_f32_16x16x32_bf16(Bt[n][k], At[m][k], acc[ai][bj][m][n], 0, 0, 0); __builtin_amdgcn_s_setprio(0); } while (0)
; #define PG8_WAIT_V(n) asm volatile("s_waitcnt vmcnt(" #n ")" ::: "memory")
; #define PG8_WAIT_L(n) asm volatile("s_waitcnt lgkmcnt(" #n ")" ::: "memory")
; #define PG8_BAR __builtin_amdgcn_s_barrier()
; #define PG8_SCHED __builtin_amdgcn_sched_barrier(0)
; template <class Epi, class Sched, bool ALIGN_EPI = false, bool SP2 = false>
; __device__ __forceinline__ void gemm_phase(PG8_LAS unsigned char* lds, const Gemm g, const Sched& S, const Epi& E) {
;     ...
;             PG8_LDA(At, 0, 1); PG8_STAGE(PG8_SB(0, 0), b2, voffB); PG8_STAGE(PG8_SB(0, 1), b2 + hstepB, voffB); PG8_STAGE(PG8_SA(0, 0), a2, voffA);
;             PG8_WAIT_V(8); PG8_WAIT_L(0); PG8_BAR; PG8_MMA(1, 0, At, B0); PG8_MMA(1, 1, At, B1); PG8_BAR; PG8_SCHED;
	s_add_i32 s29, s54, s40
	v_lshl_add_u64 v[150:151], s[22:23], 0, v[130:131]
	s_mov_b32 m0, s29
	ds_read_b128 v[192:195], v160 offset:16384
	ds_read_b128 v[196:199], v160 offset:17408
	ds_read_b128 v[200:203], v160 offset:18432
	ds_read_b128 v[204:207], v160 offset:19456
	ds_read_b128 v[208:211], v160 offset:20480
	ds_read_b128 v[212:215], v160 offset:21504
	ds_read_b128 v[216:219], v160 offset:22528
	ds_read_b128 v[220:223], v160 offset:23552
	global_load_lds_dwordx4 v[150:151], off
	s_add_i32 m0, s29, 0x2000
	s_add_u32 s30, s22, 0x40000
	v_lshl_add_u64 v[224:225], s[22:23], 0, v[134:135]
	s_addc_u32 s31, s23, 0
	s_add_i32 s29, s55, s40
	global_load_lds_dwordx4 v[224:225], off
	v_lshl_add_u64 v[226:227], s[30:31], 0, v[130:131]
	s_mov_b32 m0, s29
	v_lshl_add_u64 v[228:229], s[34:35], 0, v[132:133]
	global_load_lds_dwordx4 v[226:227], off
	v_lshl_add_u64 v[226:227], s[30:31], 0, v[134:135]
	s_add_i32 m0, s29, 0x2000
	s_nop 0
	global_load_lds_dwordx4 v[226:227], off
	v_lshl_add_u64 v[226:227], s[34:35], 0, v[128:129]
	s_mov_b32 m0, s43
	s_nop 0
	global_load_lds_dwordx4 v[226:227], off
	s_mov_b32 m0, s46
	s_nop 0
	global_load_lds_dwordx4 v[228:229], off
	s_waitcnt vmcnt(8)
	s_waitcnt lgkmcnt(0)
	s_barrier
	s_waitcnt lgkmcnt(0)
	v_mfma_f32_16x16x32_bf16 v[60:63], v[146:149], v[192:195], 0
	v_mfma_f32_16x16x32_bf16 v[56:59], v[168:171], v[192:195], 0
	v_mfma_f32_16x16x32_bf16 v[44:47], v[146:149], v[200:203], 0
	v_mfma_f32_16x16x32_bf16 v[40:43], v[168:171], v[200:203], 0
	v_mfma_f32_16x16x32_bf16 v[28:31], v[146:149], v[208:211], 0
	v_mfma_f32_16x16x32_bf16 v[24:27], v[168:171], v[208:211], 0
	v_mfma_f32_16x16x32_bf16 v[12:15], v[146:149], v[216:219], 0
	v_mfma_f32_16x16x32_bf16 v[8:11], v[168:171], v[216:219], 0
	v_mfma_f32_16x16x32_bf16 v[60:63], v[164:167], v[196:199], v[60:63]
	v_mfma_f32_16x16x32_bf16 v[56:59], v[172:175], v[196:199], v[56:59]
	v_mfma_f32_16x16x32_bf16 v[44:47], v[164:167], v[204:207], v[44:47]
	v_mfma_f32_16x16x32_bf16 v[40:43], v[172:175], v[204:207], v[40:43]
	v_mfma_f32_16x16x32_bf16 v[28:31], v[164:167], v[212:215], v[28:31]
	v_mfma_f32_16x16x32_bf16 v[24:27], v[172:175], v[212:215], v[24:27]
	v_mfma_f32_16x16x32_bf16 v[12:15], v[164:167], v[220:223], v[12:15]
	v_mfma_f32_16x16x32_bf16 v[8:11], v[172:175], v[220:223], v[8:11]
	v_mfma_f32_16x16x32_bf16 v[52:55], v[176:179], v[192:195], 0
	v_mfma_f32_16x16x32_bf16 v[48:51], v[184:187], v[192:195], 0
	v_mfma_f32_16x16x32_bf16 v[36:39], v[176:179], v[200:203], 0
	v_mfma_f32_16x16x32_bf16 v[32:35], v[184:187], v[200:203], 0
	v_mfma_f32_16x16x32_bf16 v[20:23], v[176:179], v[208:211], 0
	v_mfma_f32_16x16x32_bf16 v[16:19], v[184:187], v[208:211], 0
	v_mfma_f32_16x16x32_bf16 v[4:7], v[176:179], v[216:219], 0
	v_mfma_f32_16x16x32_bf16 v[0:3], v[184:187], v[216:219], 0
	v_mfma_f32_16x16x32_bf16 v[52:55], v[180:183], v[196:199], v[52:55]
	v_mfma_f32_16x16x32_bf16 v[48:51], v[188:191], v[196:199], v[48:51]
	v_mfma_f32_16x16x32_bf16 v[36:39], v[180:183], v[204:207], v[36:39]
	v_mfma_f32_16x16x32_bf16 v[32:35], v[188:191], v[204:207], v[32:35]
	v_mfma_f32_16x16x32_bf16 v[20:23], v[180:183], v[212:215], v[20:23]
	v_mfma_f32_16x16x32_bf16 v[16:19], v[188:191], v[212:215], v[16:19]
	v_mfma_f32_16x16x32_bf16 v[4:7], v[180:183], v[220:223], v[4:7]
	v_mfma_f32_16x16x32_bf16 v[0:3], v[188:191], v[220:223], v[0:3]
	s_barrier
	s_branch .Lkmid_P7

; #define PG8_STAGE(bufoff, gbase, voff) do { _Pragma("unroll") for (int _i = 0; _i < 2; ++_i) \
;         __builtin_amdgcn_global_load_lds((const unsigned*)((const char*)(gbase) + (voff)[_i]), (PG8_LAS unsigned*)(lds + (bufoff) + ldsw + _i * 8192), 16, 0, PG8_LOAD_AUX); } while (0)
; #define PG8_LDA(dst, b, h) do { _Pragma("unroll") for (int m = 0; m < 4; ++m) _Pragma("unroll") for (int k = 0; k < 2; ++k) dst[m][k] = *(const PG8_LAS bf16x8*)(lds + PG8_SA(b, h) + aoff + m * 2048 + k * 1024); } while (0)
; #define PG8_LDB(dst, b, h) do { _Pragma("unroll") for (int n = 0; n < 2; ++n) _Pragma("unroll") for (int k = 0; k < 2; ++k) dst[n][k] = *(const PG8_LAS bf16x8*)(lds + PG8_SB(b, h) + boff + n * 2048 + k * 1024); } while (0)
;     __host__ __device__ bool next(int i, Unit& u) const {
;         const long L = (long)i * G + c; if (L >= nwg) return false;
;         int wgid = (int)L; { const int q = nwg / NXCD, r = nwg % NXCD, xcd = wgid % NXCD, off = wgid / NXCD; wgid = (xcd < r ? xcd * (q + 1) : r * (q + 1) + (xcd - r) * q) + off; }
;         const int nig = WGM * nN, gid = wgid / nig, fm = gid * WGM, gsz = (nM - fm) < WGM ? (nM - fm) : WGM;
;         u.pm = fm + ((wgid % nig) % gsz); u.pn = (wgid % nig) / gsz; return true;
; template <class Epi, class Sched, bool ALIGN_EPI = false, bool SP2 = false>
; __device__ __forceinline__ void gemm_phase(PG8_LAS unsigned char* lds, const Gemm g, const Sched& S, const Epi& E) {
;     ...
;         const bool has_next = S.next(ui + 1, nxt);
;         const char* nA = has_next ? (const char*)g.A + (size_t)nxt.pm * tstepA + (size_t)nxt.pn * apn : cA; const char* nB = has_next ? (const char*)g.Bt + (size_t)nxt.pn * tstepB : cB;
;         for (int t = 0; t < nt; t += 2) {
;             const bool last = (t == nt - 2);
;             const char* a1 = cA + (size_t)(t + 1) * kstep;
;             const char* a2 = last ? nA : cA + (size_t)(t + 2) * kstep; const char* b2 = last ? nB : cB + (size_t)(t + 2) * kstep;
;             const char* a3 = a2 + kstep; const char* b3 = b2 + kstep;
;             if (last && has_next) S.a_ready(nxt);
;             if constexpr (SP2) {
;             PG8_LDB(B0, 0, 0); PG8_LDB(B1, 0, 1); PG8_SCHED; PG8_LDA(At, 0, 0); PG8_STAGE(PG8_SA(1, 1), a1 + hstepA, voffA);
;             PG8_WAIT_V(8); PG8_WAIT_L(0); PG8_BAR; PG8_MMA(0, 0, At, B0); PG8_MMA(0, 1, At, B1); PG8_BAR; PG8_SCHED;
.LBB0_1108:
	s_add_u32 s20, s20, 0x40080
	s_addc_u32 s21, s21, 0
	s_add_u32 s26, s22, 0x100
	s_addc_u32 s27, s23, 0
	s_mov_b32 s28, -2
	ds_read_b128 v[146:149], v157
	ds_read_b128 v[162:165], v157 offset:1024
	ds_read_b128 v[166:169], v157 offset:2048
	ds_read_b128 v[170:173], v157 offset:3072
	ds_read_b128 v[174:177], v158
	ds_read_b128 v[178:181], v158 offset:1024
	ds_read_b128 v[182:185], v158 offset:2048
	ds_read_b128 v[186:189], v158 offset:3072
	s_add_u32 s22, s20, 0xfffc0080
	s_addc_u32 s23, s21, -1
	s_cmp_eq_u32 s28, 12
	s_cselect_b32 s35, s17, s23
	s_cselect_b32 s34, s24, s22
	s_cselect_b32 s23, s15, s27
	s_cselect_b32 s22, s25, s26
	v_lshl_add_u64 v[150:151], s[20:21], 0, v[138:139]
	s_add_i32 m0, s45, 0xc000
	ds_read_b128 v[190:193], v159
	ds_read_b128 v[194:197], v159 offset:1024
	ds_read_b128 v[198:201], v159 offset:2048
	ds_read_b128 v[202:205], v159 offset:3072
	ds_read_b128 v[206:209], v159 offset:4096
	ds_read_b128 v[210:213], v159 offset:5120
	ds_read_b128 v[214:217], v159 offset:6144
	ds_read_b128 v[218:221], v159 offset:7168
	global_load_lds_dwordx4 v[150:151], off
	v_lshl_add_u64 v[150:151], s[20:21], 0, v[140:141]
	s_add_i32 m0, s45, 0xe000
	s_nop 0
	global_load_lds_dwordx4 v[150:151], off
	s_waitcnt vmcnt(8)
	s_waitcnt lgkmcnt(0)
	s_barrier
	s_waitcnt lgkmcnt(0)
	v_mfma_f32_16x16x32_bf16 v[124:127], v[146:149], v[190:193], 0
	s_add_i32 s49, s49, 1
	s_mul_i32 s2, s49, s52
	v_mfma_f32_16x16x32_bf16 v[120:123], v[166:169], v[190:193], 0
	s_mul_hi_u32 s3, s49, s53
	s_add_i32 s3, s3, s2
	v_mfma_f32_16x16x32_bf16 v[108:111], v[146:149], v[198:201], 0
	s_mul_i32 s2, s49, s53
	v_readlane_b32 s15, v239, 0
	v_mfma_f32_16x16x32_bf16 v[104:107], v[166:169], v[198:201], 0
	s_add_u32 s18, s2, s15
	s_addc_u32 s19, s3, s43
	v_mfma_f32_16x16x32_bf16 v[92:95], v[146:149], v[206:209], 0
	s_cmp_lt_u32 s18, 0xb00
	s_cselect_b64 s[2:3], -1, 0
	v_mfma_f32_16x16x32_bf16 v[88:91], v[166:169], v[206:209], 0
	s_ashr_i32 s14, s18, 31
	s_lshr_b32 s14, s14, 29
	v_mfma_f32_16x16x32_bf16 v[76:79], v[146:149], v[214:217], 0
	s_add_i32 s14, s18, s14
	s_ashr_i32 s15, s14, 3
	v_mfma_f32_16x16x32_bf16 v[72:75], v[166:169], v[214:217], 0
	s_and_b32 s14, s14, -8
	s_sub_i32 s14, s18, s14
	v_mfma_f32_16x16x32_bf16 v[124:127], v[162:165], v[194:197], v[124:127]
	s_cmp_lt_i32 s14, 0
	s_cselect_b32 s16, s44, 0x160
	v_mfma_f32_16x16x32_bf16 v[120:123], v[170:173], v[194:197], v[120:123]
	s_mul_i32 s14, s14, s16
	s_add_i32 s14, s14, s15
	v_mfma_f32_16x16x32_bf16 v[108:111], v[162:165], v[202:205], v[108:111]
	s_mul_hi_i32 s15, s14, 0x2e8ba2e9
	s_lshr_b32 s16, s15, 31
	v_mfma_f32_16x16x32_bf16 v[104:107], v[170:173], v[202:205], v[104:107]
	s_ashr_i32 s15, s15, 4
	s_add_i32 s15, s15, s16
	v_mfma_f32_16x16x32_bf16 v[92:95], v[162:165], v[210:213], v[92:95]
	s_lshl_b32 s16, s15, 2
	s_sub_i32 s17, 0x80, s16
	v_mfma_f32_16x16x32_bf16 v[88:91], v[170:173], v[210:213], v[88:91]
	s_min_i32 s17, s17, 4
	s_mulk_i32 s15, 0x58
	v_mfma_f32_16x16x32_bf16 v[76:79], v[162:165], v[218:221], v[76:79]
	s_sub_i32 s15, s14, s15
	s_lshr_b32 s14, s15, 2
	v_mfma_f32_16x16x32_bf16 v[72:75], v[170:173], v[218:221], v[72:75]
	s_and_b32 s15, s15, 3
	s_add_i32 s16, s16, s15
	v_mfma_f32_16x16x32_bf16 v[116:119], v[174:177], v[190:193], 0
	s_ashr_i32 s17, s16, 31
	s_lshl_b64 s[18:19], s[16:17], 19
	v_mfma_f32_16x16x32_bf16 v[112:115], v[182:185], v[190:193], 0
	s_add_u32 s18, s30, s18
	s_addc_u32 s19, s31, s19
	v_mfma_f32_16x16x32_bf16 v[100:103], v[174:177], v[198:201], 0
	s_sub_u32 s98, s20, 0x40080
	s_subb_u32 s99, s21, 0
	v_mfma_f32_16x16x32_bf16 v[96:99], v[182:185], v[198:201], 0
	s_cmp_lg_u64 s[2:3], 0
	s_cselect_b32 s17, s19, s99
	v_mfma_f32_16x16x32_bf16 v[84:87], v[174:177], v[206:209], 0
	s_cselect_b32 s24, s18, s98
	s_ashr_i32 s15, s14, 31
	v_mfma_f32_16x16x32_bf16 v[80:83], v[182:185], v[206:209], 0
	s_lshl_b64 s[98:99], s[14:15], 19
	s_add_u32 s36, s40, s98
	v_mfma_f32_16x16x32_bf16 v[68:71], v[174:177], v[214:217], 0
	s_addc_u32 s37, s41, s99
	s_sub_u32 s98, s26, 0x100
	v_mfma_f32_16x16x32_bf16 v[64:67], v[182:185], v[214:217], 0
	s_subb_u32 s99, s27, 0
	s_cmp_lg_u64 s[2:3], 0
	v_mfma_f32_16x16x32_bf16 v[116:119], v[178:181], v[194:197], v[116:119]
	s_cselect_b32 s15, s37, s99
	s_cselect_b32 s25, s36, s98
	v_mfma_f32_16x16x32_bf16 v[112:115], v[186:189], v[194:197], v[112:115]
	v_mfma_f32_16x16x32_bf16 v[100:103], v[178:181], v[202:205], v[100:103]
	v_mfma_f32_16x16x32_bf16 v[96:99], v[186:189], v[202:205], v[96:99]
	v_mfma_f32_16x16x32_bf16 v[84:87], v[178:181], v[210:213], v[84:87]
	v_mfma_f32_16x16x32_bf16 v[80:83], v[186:189], v[210:213], v[80:83]
	v_mfma_f32_16x16x32_bf16 v[68:71], v[178:181], v[218:221], v[68:71]
	v_mfma_f32_16x16x32_bf16 v[64:67], v[186:189], v[218:221], v[64:67]
	s_barrier
; #define PG8_STAGE(bufoff, gbase, voff) do { _Pragma("unroll") for (int _i = 0; _i < 2; ++_i) \
;         __builtin_amdgcn_global_load_lds((const unsigned*)((const char*)(gbase) + (voff)[_i]), (PG8_LAS unsigned*)(lds + (bufoff) + ldsw + _i * 8192), 16, 0, PG8_LOAD_AUX); } while (0)
; #define PG8_LDA(dst, b, h) do { _Pragma("unroll") for (int m = 0; m < 4; ++m) _Pragma("unroll") for (int k = 0; k < 2; ++k) dst[m][k] = *(const PG8_LAS bf16x8*)(lds + PG8_SA(b, h) + aoff + m * 2048 + k * 1024); } while (0)
; #define PG8_MMA(ai, bj, At, Bt) do { __builtin_amdgcn_s_setprio(1); _Pragma("unroll") for (int m = 0; m < 4; ++m) _Pragma("unroll") for (int n = 0; n < 2; ++n) _Pragma("unroll") for (int k = 0; k < 2; ++k) \
;         acc[ai][bj][m][n] = __builtin_amdgcn_mfma_f32_16x16x32_bf16(Bt[n][k], At[m][k], acc[ai][bj][m][n], 0, 0, 0); __builtin_amdgcn_s_setprio(0); } while (0)
; #define PG8_WAIT_V(n) asm volatile("s_waitcnt vmcnt(" #n ")" ::: "memory")
; #define PG8_WAIT_L(n) asm volatile("s_waitcnt lgkmcnt(" #n ")" ::: "memory")
; #define PG8_BAR __builtin_amdgcn_s_barrier()
; #define PG8_SCHED __builtin_amdgcn_sched_barrier(0)
; template <class Epi, class Sched, bool ALIGN_EPI = false, bool SP2 = false>
; __device__ __forceinline__ void gemm_phase(PG8_LAS unsigned char* lds, const Gemm g, const Sched& S, const Epi& E) {
;     ...
;             PG8_LDA(At, 0, 1); PG8_STAGE(PG8_SB(0, 0), b2, voffB); PG8_STAGE(PG8_SB(0, 1), b2 + hstepB, voffB); PG8_STAGE(PG8_SA(0, 0), a2, voffA);
;             PG8_WAIT_V(8); PG8_WAIT_L(0); PG8_BAR; PG8_MMA(1, 0, At, B0); PG8_MMA(1, 1, At, B1); PG8_BAR; PG8_SCHED;
	s_add_i32 s29, s54, s42
	v_lshl_add_u64 v[150:151], s[22:23], 0, v[132:133]
	s_mov_b32 m0, s29
	ds_read_b128 v[190:193], v159 offset:16384
	ds_read_b128 v[194:197], v159 offset:17408
	ds_read_b128 v[198:201], v159 offset:18432
	ds_read_b128 v[202:205], v159 offset:19456
	ds_read_b128 v[206:209], v159 offset:20480
	ds_read_b128 v[210:213], v159 offset:21504
	ds_read_b128 v[214:217], v159 offset:22528
	ds_read_b128 v[218:221], v159 offset:23552
	global_load_lds_dwordx4 v[150:151], off
	s_add_i32 m0, s29, 0x2000
	s_add_u32 s30, s22, 0x40000
	v_lshl_add_u64 v[222:223], s[22:23], 0, v[128:129]
	s_addc_u32 s31, s23, 0
	s_add_i32 s29, s55, s42
	global_load_lds_dwordx4 v[222:223], off
	v_lshl_add_u64 v[224:225], s[30:31], 0, v[132:133]
	s_mov_b32 m0, s29
	v_lshl_add_u64 v[226:227], s[34:35], 0, v[130:131]
	global_load_lds_dwordx4 v[224:225], off
	v_lshl_add_u64 v[224:225], s[30:31], 0, v[128:129]
	s_add_i32 m0, s29, 0x2000
	s_nop 0
	global_load_lds_dwordx4 v[224:225], off
	v_lshl_add_u64 v[224:225], s[34:35], 0, v[134:135]
	s_mov_b32 m0, s45
	s_nop 0
	global_load_lds_dwordx4 v[224:225], off
	s_mov_b32 m0, s46
	s_nop 0
	global_load_lds_dwordx4 v[226:227], off
	s_waitcnt vmcnt(8)
	s_waitcnt lgkmcnt(0)
	s_barrier
	s_waitcnt lgkmcnt(0)
	v_mfma_f32_16x16x32_bf16 v[60:63], v[146:149], v[190:193], 0
	v_mfma_f32_16x16x32_bf16 v[56:59], v[166:169], v[190:193], 0
	v_mfma_f32_16x16x32_bf16 v[44:47], v[146:149], v[198:201], 0
	v_mfma_f32_16x16x32_bf16 v[40:43], v[166:169], v[198:201], 0
	v_mfma_f32_16x16x32_bf16 v[28:31], v[146:149], v[206:209], 0
	v_mfma_f32_16x16x32_bf16 v[24:27], v[166:169], v[206:209], 0
	v_mfma_f32_16x16x32_bf16 v[12:15], v[146:149], v[214:217], 0
	v_mfma_f32_16x16x32_bf16 v[8:11], v[166:169], v[214:217], 0
	v_mfma_f32_16x16x32_bf16 v[60:63], v[162:165], v[194:197], v[60:63]
	v_mfma_f32_16x16x32_bf16 v[56:59], v[170:173], v[194:197], v[56:59]
	v_mfma_f32_16x16x32_bf16 v[44:47], v[162:165], v[202:205], v[44:47]
	v_mfma_f32_16x16x32_bf16 v[40:43], v[170:173], v[202:205], v[40:43]
	v_mfma_f32_16x16x32_bf16 v[28:31], v[162:165], v[210:213], v[28:31]
	v_mfma_f32_16x16x32_bf16 v[24:27], v[170:173], v[210:213], v[24:27]
	v_mfma_f32_16x16x32_bf16 v[12:15], v[162:165], v[218:221], v[12:15]
	v_mfma_f32_16x16x32_bf16 v[8:11], v[170:173], v[218:221], v[8:11]
	v_mfma_f32_16x16x32_bf16 v[52:55], v[174:177], v[190:193], 0
	v_mfma_f32_16x16x32_bf16 v[48:51], v[182:185], v[190:193], 0
	v_mfma_f32_16x16x32_bf16 v[36:39], v[174:177], v[198:201], 0
	v_mfma_f32_16x16x32_bf16 v[32:35], v[182:185], v[198:201], 0
	v_mfma_f32_16x16x32_bf16 v[20:23], v[174:177], v[206:209], 0
	v_mfma_f32_16x16x32_bf16 v[16:19], v[182:185], v[206:209], 0
	v_mfma_f32_16x16x32_bf16 v[4:7], v[174:177], v[214:217], 0
	v_mfma_f32_16x16x32_bf16 v[0:3], v[182:185], v[214:217], 0
	v_mfma_f32_16x16x32_bf16 v[52:55], v[178:181], v[194:197], v[52:55]
	v_mfma_f32_16x16x32_bf16 v[48:51], v[186:189], v[194:197], v[48:51]
	v_mfma_f32_16x16x32_bf16 v[36:39], v[178:181], v[202:205], v[36:39]
	v_mfma_f32_16x16x32_bf16 v[32:35], v[186:189], v[202:205], v[32:35]
	v_mfma_f32_16x16x32_bf16 v[20:23], v[178:181], v[210:213], v[20:23]
	v_mfma_f32_16x16x32_bf16 v[16:19], v[186:189], v[210:213], v[16:19]
	v_mfma_f32_16x16x32_bf16 v[4:7], v[178:181], v[218:221], v[4:7]
	v_mfma_f32_16x16x32_bf16 v[0:3], v[186:189], v[218:221], v[0:3]
	s_barrier
	s_branch .Lkmid_P12
